# prologue weight transposes: counted vmcnt ladder so previous tile stores stay in flight while next tile loads are consumed
# baseline (speedup 1.0000x reference)
; __device__ __forceinline__ int tid_() { int t = threadIdx.x; asm volatile("" : "+v"(t)); return t; }
; __device__ void transpose_job(const int bid, const int nblk, float* tile, const float* __restrict__ src, bf16_t* __restrict__ dst, int K, int N, int nb, long dstB, float scale) {
;     const int tk = K / 64, tn = N / 64, per = tk * tn, tot = per * nb, tid = tid_();
;     const int kk = tid >> 6, nn = tid & 63;
;     float r[8];
;     int t = bid;
;     if (t < tot) { const int b = t / per, l = t - b * per, k0 = (l / tn) * 64, n0 = (l % tn) * 64; const float* s = src + (long)b * K * N;
; #pragma unroll
;         for (int i = 0; i < 8; ++i) r[i] = s[(long)(k0 + kk + 8 * i) * N + n0 + nn]; }
.LBB0_299:
	s_andn2_b64 vcc, exec, s[4:5]
	s_cbranch_vccnz .LBB0_404
	s_waitcnt lgkmcnt(0)
	v_readlane_b32 s2, v254, 29
	v_mov_b32_e32 v0, v169
	s_cmpk_gt_i32 s2, 0xff
	s_movk_i32 s17, 0x5800
	s_mov_b32 s18, 0x18000
	s_mov_b32 s19, 0x20000
	s_mov_b32 s20, 0x28000
	s_mov_b32 s21, 0x30000
	s_movk_i32 s22, 0x104
	s_mov_b32 s24, 0x7f800000
	s_brev_b32 s41, 1
	s_mov_b32 s68, 0x3a800000
	v_readlane_b32 s3, v254, 30
	s_cbranch_scc1 .LBB0_305
	v_readlane_b32 s4, v254, 29
	s_mov_b32 s6, s4
	s_ashr_i32 s4, s4, 31
	v_readlane_b32 s5, v254, 30
	s_lshr_b32 s4, s4, 24
	s_add_i32 s5, s6, s4
	s_ashr_i32 s4, s5, 8
	s_and_b32 s5, s5, 0xffffff00
	s_sub_i32 s5, s6, s5
	s_ashr_i32 s6, s5, 31
	s_lshr_b32 s6, s6, 28
	s_load_dwordx2 s[2:3], s[26:27], 0x28
	s_add_i32 s6, s5, s6
	s_lshl_b32 s7, s6, 2
	s_and_b32 s6, s6, 0x3fffff0
	s_sub_i32 s5, s5, s6
	s_lshl_b32 s6, s5, 6
	s_ashr_i32 s5, s4, 31
	s_andn2_b32 s7, s7, 63
	s_lshl_b64 s[4:5], s[4:5], 22
	v_ashrrev_i32_e32 v2, 6, v0
	s_waitcnt lgkmcnt(0)
	s_add_u32 s8, s2, s4
	v_and_b32_e32 v16, 63, v0
	s_addc_u32 s9, s3, s5
	v_add_u32_e32 v0, s7, v2
	s_ashr_i32 s7, s6, 31
	s_lshl_b64 s[4:5], s[6:7], 2
	s_add_u32 s4, s8, s4
	s_addc_u32 s5, s9, s5
	v_lshlrev_b32_e32 v10, 2, v16
	v_ashrrev_i32_e32 v1, 31, v0
	v_lshl_add_u64 v[4:5], s[4:5], 0, v[10:11]
	v_lshlrev_b64 v[0:1], 12, v[0:1]
	v_lshl_add_u64 v[0:1], v[4:5], 0, v[0:1]
	v_add_co_u32_e32 v4, vcc, s0, v0
	global_load_dword v3, v[0:1], off
	s_nop 0
	v_addc_co_u32_e32 v5, vcc, 0, v1, vcc
	v_add_co_u32_e32 v6, vcc, s96, v0
	global_load_dword v4, v[4:5], off
	s_nop 0
	v_addc_co_u32_e32 v7, vcc, 0, v1, vcc
	global_load_dword v5, v[6:7], off
	v_add_co_u32_e32 v6, vcc, s18, v0
	s_mov_b32 s4, 0x38000
	s_nop 0
	v_addc_co_u32_e32 v7, vcc, 0, v1, vcc
	v_add_co_u32_e32 v8, vcc, s19, v0
	global_load_dword v6, v[6:7], off
	s_nop 0
	v_addc_co_u32_e32 v9, vcc, 0, v1, vcc
	global_load_dword v7, v[8:9], off
	v_add_co_u32_e32 v8, vcc, s20, v0
	v_add_u32_e32 v14, 0, v10
	s_nop 0
	v_addc_co_u32_e32 v9, vcc, 0, v1, vcc
	v_add_co_u32_e32 v12, vcc, s21, v0
	global_load_dword v8, v[8:9], off
	s_nop 0
	v_addc_co_u32_e32 v13, vcc, 0, v1, vcc
	v_add_co_u32_e32 v0, vcc, s4, v0
	global_load_dword v9, v[12:13], off
	s_nop 0
	v_addc_co_u32_e32 v1, vcc, 0, v1, vcc
	global_load_dword v12, v[0:1], off
	s_load_dwordx2 s[4:5], s[26:27], 0xe0
	v_lshlrev_b32_e32 v0, 8, v16
	v_lshlrev_b32_e32 v1, 2, v2
	v_lshlrev_b32_e32 v10, 1, v16
	v_add3_u32 v13, v14, v0, v1
	v_mul_lo_u32 v15, v2, s22
	s_waitcnt lgkmcnt(0)
	v_lshl_add_u64 v[0:1], s[4:5], 0, v[10:11]
	s_lshl_b32 s4, s62, 1
	s_add_i32 s4, s89, s4
	v_add_u32_e32 v14, v14, v15
	v_lshlrev_b32_e32 v10, 2, v16
	s_mov_b32 s5, s75
	s_waitcnt vmcnt(0)
	s_branch .LBB0_303

; __device__ __forceinline__ int tid_() { int t = threadIdx.x; asm volatile("" : "+v"(t)); return t; }
; __device__ void transpose_job(const int bid, const int nblk, float* tile, const float* __restrict__ src, bf16_t* __restrict__ dst, int K, int N, int nb, long dstB, float scale) {
;     const int tk = K / 64, tn = N / 64, per = tk * tn, tot = per * nb, tid = tid_();
;     const int kk = tid >> 6, nn = tid & 63;
;     float r[8];
;     int t = bid;
;     if (t < tot) { const int b = t / per, l = t - b * per, k0 = (l / tn) * 64, n0 = (l % tn) * 64; const float* s = src + (long)b * K * N;
; #pragma unroll
;         for (int i = 0; i < 8; ++i) r[i] = s[(long)(k0 + kk + 8 * i) * N + n0 + nn]; }
;     while (t < tot) {
;         const int b = t / per, l = t - b * per, k0 = (l / tn) * 64, n0 = (l % tn) * 64;
;         bf16_t* d = dst + (long)b * dstB;
; #pragma unroll
;         for (int i = 0; i < 8; ++i) tile[(kk + 8 * i) * 65 + nn] = r[i];
;         __syncthreads();
;         const int t2 = t + nblk;
;         if (t2 < tot) { const int b2 = t2 / per, l2 = t2 - b2 * per, k2 = (l2 / tn) * 64, n2 = (l2 % tn) * 64; const float* s2 = src + (long)b2 * K * N;
; #pragma unroll
;             for (int i = 0; i < 8; ++i) r[i] = s2[(long)(k2 + kk + 8 * i) * N + n2 + nn]; }
.LBB0_303:
	s_add_i32 s6, s4, s5
	s_cmpk_gt_i32 s6, 0xff
	s_waitcnt vmcnt(15)
	ds_write_b32 v14, v3
	s_waitcnt vmcnt(14)
	ds_write_b32 v14, v4 offset:2080
	s_waitcnt vmcnt(13)
	ds_write_b32 v14, v5 offset:4160
	s_waitcnt vmcnt(12)
	ds_write_b32 v14, v6 offset:6240
	s_waitcnt vmcnt(11)
	ds_write_b32 v14, v7 offset:8320
	s_waitcnt vmcnt(10)
	ds_write_b32 v14, v8 offset:10400
	s_waitcnt vmcnt(8)
	ds_write_b32 v14, v9 offset:12480
	s_waitcnt vmcnt(8)
	ds_write_b32 v14, v12 offset:14560
	s_waitcnt lgkmcnt(0)
	s_barrier
	s_cbranch_scc1 .LBB0_302
	s_ashr_i32 s7, s6, 31
	s_lshr_b32 s7, s7, 24
	s_add_i32 s7, s6, s7
	s_ashr_i32 s8, s7, 8
	s_and_b32 s7, s7, 0xffffff00
	s_sub_i32 s6, s6, s7
	s_ashr_i32 s7, s6, 31
	s_lshr_b32 s7, s7, 28
	s_add_i32 s7, s6, s7
	s_lshl_b32 s9, s7, 2
	s_and_b32 s7, s7, 0x3fffff0
	s_and_b32 s10, s9, 0xffffffc0
	s_sub_i32 s6, s6, s7
	s_ashr_i32 s9, s8, 31
	s_lshl_b32 s6, s6, 6
	s_lshl_b64 s[8:9], s[8:9], 22
	s_add_u32 s8, s2, s8
	s_addc_u32 s9, s3, s9
	s_ashr_i32 s7, s6, 31
	s_lshl_b64 s[6:7], s[6:7], 2
	v_add_u32_e32 v4, s10, v2
	s_add_u32 s6, s8, s6
	s_addc_u32 s7, s9, s7
	v_ashrrev_i32_e32 v5, 31, v4
	v_lshl_add_u64 v[6:7], s[6:7], 0, v[10:11]
	v_lshlrev_b64 v[4:5], 12, v[4:5]
	v_lshl_add_u64 v[16:17], v[6:7], 0, v[4:5]
	v_add_co_u32_e32 v4, vcc, s0, v16
	global_load_dword v3, v[16:17], off
	s_nop 0
	v_addc_co_u32_e32 v5, vcc, 0, v17, vcc
	v_add_co_u32_e32 v6, vcc, s96, v16
	global_load_dword v4, v[4:5], off
	s_nop 0
	v_addc_co_u32_e32 v7, vcc, 0, v17, vcc
	global_load_dword v5, v[6:7], off
	v_add_co_u32_e32 v6, vcc, s18, v16
	s_nop 1
	v_addc_co_u32_e32 v7, vcc, 0, v17, vcc
	v_add_co_u32_e32 v8, vcc, 0x20000, v16
	global_load_dword v6, v[6:7], off
	s_nop 0
	v_addc_co_u32_e32 v9, vcc, 0, v17, vcc
	global_load_dword v7, v[8:9], off
	v_add_co_u32_e32 v8, vcc, 0x28000, v16
	s_nop 1
	v_addc_co_u32_e32 v9, vcc, 0, v17, vcc
	v_add_co_u32_e32 v18, vcc, 0x30000, v16
	global_load_dword v8, v[8:9], off
	s_nop 0
	v_addc_co_u32_e32 v19, vcc, 0, v17, vcc
	v_add_co_u32_e32 v16, vcc, 0x38000, v16
	s_nop 1
	v_addc_co_u32_e32 v17, vcc, 0, v17, vcc
	global_load_dword v12, v[16:17], off
	global_load_dword v9, v[18:19], off
	s_branch .LBB0_302
.LBB0_305:
	v_readlane_b32 s8, v254, 29
	v_mov_b32_e32 v0, v169
	s_cmpk_gt_i32 s8, 0x27f
	s_mul_hi_i32 s4, s8, 0x66666667
	v_readlane_b32 s9, v254, 30
	s_cbranch_scc1 .LBB0_311
	s_lshr_b32 s5, s4, 31
	s_ashr_i32 s6, s4, 8
	s_add_i32 s5, s6, s5
	s_mul_i32 s6, s5, 0xfffffd80
	s_add_i32 s6, s6, s8
	s_mul_hi_i32 s7, s6, 0x66666667
	s_load_dwordx2 s[2:3], s[26:27], 0x38
	s_lshr_b32 s8, s7, 31
	s_ashr_i32 s7, s7, 4
	s_add_i32 s7, s7, s8
	s_mul_i32 s8, s7, 40
	s_sub_i32 s6, s6, s8
	s_lshl_b32 s6, s6, 6
	s_mul_hi_i32 s8, s5, 0xa00000
	s_mul_i32 s5, s5, 0xa00000
	v_ashrrev_i32_e32 v2, 6, v0
	s_waitcnt lgkmcnt(0)
	s_add_u32 s5, s2, s5
	s_addc_u32 s8, s3, s8
	v_lshl_add_u32 v14, s7, 6, v2
	s_ashr_i32 s7, s6, 31
	s_lshl_b64 s[6:7], s[6:7], 2
	v_and_b32_e32 v16, 63, v0
	s_add_u32 s6, s5, s6
	s_addc_u32 s7, s8, s7
	v_lshlrev_b32_e32 v10, 2, v16
	v_lshl_add_u64 v[0:1], s[6:7], 0, v[10:11]
	s_movk_i32 s5, 0x2800
	s_waitcnt vmcnt(0)
	v_mad_i64_i32 v[4:5], s[6:7], v14, s5, v[0:1]
	global_load_dword v3, v[4:5], off
	v_add_u32_e32 v4, 8, v14
	v_mad_i64_i32 v[4:5], s[6:7], v4, s5, v[0:1]
	global_load_dword v4, v[4:5], off
	v_add_u32_e32 v5, 16, v14
	s_waitcnt vmcnt(13)
	v_mad_i64_i32 v[6:7], s[6:7], v5, s5, v[0:1]
	global_load_dword v5, v[6:7], off
	v_add_u32_e32 v6, 24, v14
	v_mad_i64_i32 v[6:7], s[6:7], v6, s5, v[0:1]
	global_load_dword v6, v[6:7], off
	v_add_u32_e32 v7, 32, v14
	s_waitcnt vmcnt(12)
	v_mad_i64_i32 v[8:9], s[6:7], v7, s5, v[0:1]
	global_load_dword v7, v[8:9], off
	v_add_u32_e32 v8, 40, v14
	v_mad_i64_i32 v[8:9], s[6:7], v8, s5, v[0:1]
	global_load_dword v8, v[8:9], off
	v_add_u32_e32 v9, 48, v14
	v_mad_i64_i32 v[12:13], s[6:7], v9, s5, v[0:1]
	global_load_dword v9, v[12:13], off
	v_add_u32_e32 v12, 56, v14
	v_mad_i64_i32 v[0:1], s[6:7], v12, s5, v[0:1]
	global_load_dword v12, v[0:1], off
	s_load_dwordx2 s[6:7], s[26:27], 0xe8
	v_add_u32_e32 v14, 0, v10
	v_lshlrev_b32_e32 v0, 8, v16
	v_lshlrev_b32_e32 v1, 2, v2
	v_mul_lo_u32 v15, v2, s22
	v_lshlrev_b32_e32 v10, 1, v16
	s_lshl_b32 s5, s62, 1
	v_add3_u32 v13, v14, v0, v1
	s_waitcnt lgkmcnt(0)
	v_lshl_add_u64 v[0:1], s[6:7], 0, v[10:11]
	s_add_i32 s5, s89, s5
	v_add_u32_e32 v14, v14, v15
	v_lshlrev_b32_e32 v10, 2, v16
	s_mov_b32 s6, s75
	s_waitcnt vmcnt(0)
	s_branch .LBB0_308

; __device__ void transpose_job(const int bid, const int nblk, float* tile, const float* __restrict__ src, bf16_t* __restrict__ dst, int K, int N, int nb, long dstB, float scale) {
;     ...
;     while (t < tot) {
;         const int b = t / per, l = t - b * per, k0 = (l / tn) * 64, n0 = (l % tn) * 64;
;         bf16_t* d = dst + (long)b * dstB;
; #pragma unroll
;         for (int i = 0; i < 8; ++i) tile[(kk + 8 * i) * 65 + nn] = r[i];
;         __syncthreads();
;         const int t2 = t + nblk;
;         if (t2 < tot) { const int b2 = t2 / per, l2 = t2 - b2 * per, k2 = (l2 / tn) * 64, n2 = (l2 % tn) * 64; const float* s2 = src + (long)b2 * K * N;
; #pragma unroll
;             for (int i = 0; i < 8; ++i) r[i] = s2[(long)(k2 + kk + 8 * i) * N + n2 + nn]; }
.LBB0_308:
	s_add_i32 s7, s5, s6
	s_cmpk_gt_i32 s7, 0x27f
	s_waitcnt vmcnt(15)
	ds_write_b32 v14, v3
	s_waitcnt vmcnt(14)
	ds_write_b32 v14, v4 offset:2080
	s_waitcnt vmcnt(13)
	ds_write_b32 v14, v5 offset:4160
	s_waitcnt vmcnt(12)
	ds_write_b32 v14, v6 offset:6240
	s_waitcnt vmcnt(11)
	ds_write_b32 v14, v7 offset:8320
	s_waitcnt vmcnt(10)
	ds_write_b32 v14, v8 offset:10400
	s_waitcnt vmcnt(9)
	ds_write_b32 v14, v9 offset:12480
	s_waitcnt vmcnt(8)
	ds_write_b32 v14, v12 offset:14560
	s_waitcnt lgkmcnt(0)
	s_barrier
	s_cbranch_scc1 .LBB0_307
	s_mul_hi_i32 s8, s7, 0x66666667
	s_lshr_b32 s9, s8, 31
	s_ashr_i32 s8, s8, 8
	s_add_i32 s9, s8, s9
	s_mul_i32 s8, s9, 0xfffffd80
	s_add_i32 s7, s7, s8
	s_mul_hi_i32 s8, s7, 0x66666667
	s_lshr_b32 s10, s8, 31
	s_ashr_i32 s8, s8, 4
	s_add_i32 s10, s8, s10
	s_mul_i32 s8, s10, 40
	s_sub_i32 s7, s7, s8
	s_lshl_b32 s8, s7, 6
	s_mul_hi_i32 s7, s9, 0xa00000
	s_mul_i32 s9, s9, 0xa00000
	s_add_u32 s11, s2, s9
	s_addc_u32 s7, s3, s7
	s_ashr_i32 s9, s8, 31
	s_lshl_b64 s[8:9], s[8:9], 2
	s_add_u32 s8, s11, s8
	s_addc_u32 s9, s7, s9
	v_lshl_add_u32 v12, s10, 6, v2
	v_lshl_add_u64 v[16:17], s[8:9], 0, v[10:11]
	s_movk_i32 s7, 0x2800
	v_mad_i64_i32 v[4:5], s[8:9], v12, s7, v[16:17]
	global_load_dword v3, v[4:5], off
	v_add_u32_e32 v4, 8, v12
	v_mad_i64_i32 v[4:5], s[8:9], v4, s7, v[16:17]
	global_load_dword v4, v[4:5], off
	v_add_u32_e32 v5, 16, v12
	v_mad_i64_i32 v[6:7], s[8:9], v5, s7, v[16:17]
	global_load_dword v5, v[6:7], off
	v_add_u32_e32 v6, 24, v12
	v_mad_i64_i32 v[6:7], s[8:9], v6, s7, v[16:17]
	global_load_dword v6, v[6:7], off
	v_add_u32_e32 v7, 32, v12
	v_mad_i64_i32 v[8:9], s[8:9], v7, s7, v[16:17]
	global_load_dword v7, v[8:9], off
	v_add_u32_e32 v8, 40, v12
	v_mad_i64_i32 v[8:9], s[8:9], v8, s7, v[16:17]
	global_load_dword v8, v[8:9], off
	v_add_u32_e32 v9, 48, v12
	v_add_u32_e32 v12, 56, v12
	v_mad_i64_i32 v[18:19], s[8:9], v9, s7, v[16:17]
	v_mad_i64_i32 v[16:17], s[8:9], v12, s7, v[16:17]
	global_load_dword v9, v[18:19], off
	global_load_dword v12, v[16:17], off
	s_branch .LBB0_307

; __device__ __forceinline__ int tid_() { int t = threadIdx.x; asm volatile("" : "+v"(t)); return t; }
; __device__ void transpose_job(const int bid, const int nblk, float* tile, const float* __restrict__ src, bf16_t* __restrict__ dst, int K, int N, int nb, long dstB, float scale) {
;     const int tk = K / 64, tn = N / 64, per = tk * tn, tot = per * nb, tid = tid_();
;     const int kk = tid >> 6, nn = tid & 63;
;     float r[8];
;     int t = bid;
;     if (t < tot) { const int b = t / per, l = t - b * per, k0 = (l / tn) * 64, n0 = (l % tn) * 64; const float* s = src + (long)b * K * N;
; #pragma unroll
;         for (int i = 0; i < 8; ++i) r[i] = s[(long)(k0 + kk + 8 * i) * N + n0 + nn]; }
.LBB0_311:
	v_mov_b32_e32 v0, v169
	s_cmpk_gt_i32 s8, 0x13f
	s_cbranch_scc1 .LBB0_317
	s_lshr_b32 s5, s4, 31
	s_ashr_i32 s4, s4, 7
	s_add_i32 s5, s4, s5
	s_mul_i32 s4, s5, 0xfffffec0
	s_add_i32 s4, s4, s8
	s_ashr_i32 s6, s4, 31
	s_load_dwordx2 s[2:3], s[26:27], 0x78
	s_lshr_b32 s6, s6, 28
	s_add_i32 s6, s4, s6
	s_lshl_b32 s7, s6, 2
	s_and_b32 s6, s6, 0x3fffff0
	s_sub_i32 s4, s4, s6
	s_andn2_b32 s7, s7, 63
	s_lshl_b32 s4, s4, 6
	s_mul_hi_i32 s6, s5, 0x500000
	s_mul_i32 s5, s5, 0x500000
	s_waitcnt lgkmcnt(0)
	s_add_u32 s8, s2, s5
	s_addc_u32 s6, s3, s6
	s_ashr_i32 s5, s4, 31
	v_ashrrev_i32_e32 v2, 6, v0
	s_lshl_b64 s[4:5], s[4:5], 2
	v_and_b32_e32 v16, 63, v0
	v_add_u32_e32 v0, s7, v2
	s_add_u32 s4, s8, s4
	s_addc_u32 s5, s6, s5
	v_lshlrev_b32_e32 v10, 2, v16
	v_ashrrev_i32_e32 v1, 31, v0
	s_waitcnt vmcnt(0)
	v_lshl_add_u64 v[4:5], s[4:5], 0, v[10:11]
	v_lshlrev_b64 v[0:1], 12, v[0:1]
	v_lshl_add_u64 v[0:1], v[4:5], 0, v[0:1]
	v_add_co_u32_e32 v4, vcc, s0, v0
	global_load_dword v3, v[0:1], off
	s_nop 0
	v_addc_co_u32_e32 v5, vcc, 0, v1, vcc
	s_waitcnt vmcnt(13)
	v_add_co_u32_e32 v6, vcc, s96, v0
	global_load_dword v4, v[4:5], off
	s_waitcnt vmcnt(13)
	v_addc_co_u32_e32 v7, vcc, 0, v1, vcc
	global_load_dword v5, v[6:7], off
	v_add_co_u32_e32 v6, vcc, s18, v0
	s_mov_b32 s4, 0x38000
	s_nop 0
	v_addc_co_u32_e32 v7, vcc, 0, v1, vcc
	s_waitcnt vmcnt(13)
	v_add_co_u32_e32 v8, vcc, s19, v0
	global_load_dword v6, v[6:7], off
	s_waitcnt vmcnt(12)
	v_addc_co_u32_e32 v9, vcc, 0, v1, vcc
	global_load_dword v7, v[8:9], off
	v_add_co_u32_e32 v8, vcc, s20, v0
	v_add_u32_e32 v14, 0, v10
	s_nop 0
	v_addc_co_u32_e32 v9, vcc, 0, v1, vcc
	v_add_co_u32_e32 v12, vcc, s21, v0
	global_load_dword v8, v[8:9], off
	s_nop 0
	v_addc_co_u32_e32 v13, vcc, 0, v1, vcc
	v_add_co_u32_e32 v0, vcc, s4, v0
	global_load_dword v9, v[12:13], off
	s_nop 0
	v_addc_co_u32_e32 v1, vcc, 0, v1, vcc
	global_load_dword v12, v[0:1], off
	s_load_dwordx2 s[4:5], s[26:27], 0xf8
	v_lshlrev_b32_e32 v0, 8, v16
	v_lshlrev_b32_e32 v1, 2, v2
	v_lshlrev_b32_e32 v10, 1, v16
	v_add3_u32 v13, v14, v0, v1
	v_mul_lo_u32 v15, v2, s22
	s_waitcnt lgkmcnt(0)
	v_lshl_add_u64 v[0:1], s[4:5], 0, v[10:11]
	s_lshl_b32 s4, s62, 1
	s_add_i32 s4, s89, s4
	v_add_u32_e32 v14, v14, v15
	v_lshlrev_b32_e32 v10, 2, v16
	s_mov_b32 s5, s75
	s_waitcnt vmcnt(0)
	s_branch .LBB0_314

; __device__ void transpose_job(const int bid, const int nblk, float* tile, const float* __restrict__ src, bf16_t* __restrict__ dst, int K, int N, int nb, long dstB, float scale) {
;     ...
;     while (t < tot) {
;         const int b = t / per, l = t - b * per, k0 = (l / tn) * 64, n0 = (l % tn) * 64;
;         bf16_t* d = dst + (long)b * dstB;
; #pragma unroll
;         for (int i = 0; i < 8; ++i) tile[(kk + 8 * i) * 65 + nn] = r[i];
;         __syncthreads();
;         const int t2 = t + nblk;
;         if (t2 < tot) { const int b2 = t2 / per, l2 = t2 - b2 * per, k2 = (l2 / tn) * 64, n2 = (l2 % tn) * 64; const float* s2 = src + (long)b2 * K * N;
; #pragma unroll
;             for (int i = 0; i < 8; ++i) r[i] = s2[(long)(k2 + kk + 8 * i) * N + n2 + nn]; }
.LBB0_314:
	s_add_i32 s6, s4, s5
	s_cmpk_gt_i32 s6, 0x13f
	s_waitcnt vmcnt(15)
	ds_write_b32 v14, v3
	s_waitcnt vmcnt(14)
	ds_write_b32 v14, v4 offset:2080
	s_waitcnt vmcnt(13)
	ds_write_b32 v14, v5 offset:4160
	s_waitcnt vmcnt(12)
	ds_write_b32 v14, v6 offset:6240
	s_waitcnt vmcnt(11)
	ds_write_b32 v14, v7 offset:8320
	s_waitcnt vmcnt(10)
	ds_write_b32 v14, v8 offset:10400
	s_waitcnt vmcnt(8)
	ds_write_b32 v14, v9 offset:12480
	s_waitcnt vmcnt(8)
	ds_write_b32 v14, v12 offset:14560
	s_waitcnt lgkmcnt(0)
	s_barrier
	s_cbranch_scc1 .LBB0_313
	s_mul_hi_i32 s7, s6, 0x66666667
	s_lshr_b32 s8, s7, 31
	s_ashr_i32 s7, s7, 7
	s_add_i32 s7, s7, s8
	s_mul_i32 s8, s7, 0xfffffec0
	s_add_i32 s6, s6, s8
	s_ashr_i32 s8, s6, 31
	s_lshr_b32 s8, s8, 28
	s_add_i32 s8, s6, s8
	s_lshl_b32 s9, s8, 2
	s_and_b32 s8, s8, 0x3fffff0
	s_sub_i32 s6, s6, s8
	s_andn2_b32 s9, s9, 63
	s_lshl_b32 s6, s6, 6
	s_mul_hi_i32 s8, s7, 0x500000
	s_mul_i32 s7, s7, 0x500000
	s_add_u32 s10, s2, s7
	s_addc_u32 s8, s3, s8
	s_ashr_i32 s7, s6, 31
	s_lshl_b64 s[6:7], s[6:7], 2
	v_add_u32_e32 v4, s9, v2
	s_add_u32 s6, s10, s6
	s_addc_u32 s7, s8, s7
	v_ashrrev_i32_e32 v5, 31, v4
	v_lshl_add_u64 v[6:7], s[6:7], 0, v[10:11]
	v_lshlrev_b64 v[4:5], 12, v[4:5]
	v_lshl_add_u64 v[16:17], v[6:7], 0, v[4:5]
	v_add_co_u32_e32 v4, vcc, s0, v16
	global_load_dword v3, v[16:17], off
	s_nop 0
	v_addc_co_u32_e32 v5, vcc, 0, v17, vcc
	v_add_co_u32_e32 v6, vcc, s96, v16
	global_load_dword v4, v[4:5], off
	s_nop 0
	v_addc_co_u32_e32 v7, vcc, 0, v17, vcc
	global_load_dword v5, v[6:7], off
	v_add_co_u32_e32 v6, vcc, s18, v16
	s_nop 1
	v_addc_co_u32_e32 v7, vcc, 0, v17, vcc
	v_add_co_u32_e32 v8, vcc, 0x20000, v16
	global_load_dword v6, v[6:7], off
	s_nop 0
	v_addc_co_u32_e32 v9, vcc, 0, v17, vcc
	global_load_dword v7, v[8:9], off
	v_add_co_u32_e32 v8, vcc, 0x28000, v16
	s_nop 1
	v_addc_co_u32_e32 v9, vcc, 0, v17, vcc
	v_add_co_u32_e32 v18, vcc, 0x30000, v16
	global_load_dword v8, v[8:9], off
	s_nop 0
	v_addc_co_u32_e32 v19, vcc, 0, v17, vcc
	v_add_co_u32_e32 v16, vcc, 0x38000, v16
	s_nop 1
	v_addc_co_u32_e32 v17, vcc, 0, v17, vcc
	global_load_dword v12, v[16:17], off
	global_load_dword v9, v[18:19], off
	s_branch .LBB0_313

; __device__ __forceinline__ int tid_() { int t = threadIdx.x; asm volatile("" : "+v"(t)); return t; }
; __device__ void transpose_job(const int bid, const int nblk, float* tile, const float* __restrict__ src, bf16_t* __restrict__ dst, int K, int N, int nb, long dstB, float scale) {
;     const int tk = K / 64, tn = N / 64, per = tk * tn, tot = per * nb, tid = tid_();
;     const int kk = tid >> 6, nn = tid & 63;
;     float r[8];
;     int t = bid;
;     if (t < tot) { const int b = t / per, l = t - b * per, k0 = (l / tn) * 64, n0 = (l % tn) * 64; const float* s = src + (long)b * K * N;
; #pragma unroll
;         for (int i = 0; i < 8; ++i) r[i] = s[(long)(k0 + kk + 8 * i) * N + n0 + nn]; }
.LBB0_317:
	s_cmpk_lt_i32 s8, 0x200
	v_mov_b32_e32 v0, v169
	s_cselect_b64 s[2:3], -1, 0
	s_cmpk_gt_i32 s8, 0x1ff
	s_cbranch_scc1 .LBB0_323
	s_ashr_i32 s6, s8, 31
	s_lshr_b32 s6, s6, 24
	s_add_i32 s7, s8, s6
	s_ashr_i32 s6, s7, 8
	s_and_b32 s7, s7, 0xffffff00
	s_sub_i32 s7, s8, s7
	s_ashr_i32 s8, s7, 31
	s_lshr_b32 s8, s8, 28
	s_load_dwordx2 s[4:5], s[26:27], 0x90
	s_add_i32 s8, s7, s8
	s_lshl_b32 s9, s8, 2
	s_and_b32 s8, s8, 0x3fffff0
	s_sub_i32 s7, s7, s8
	s_lshl_b32 s8, s7, 6
	s_ashr_i32 s7, s6, 31
	s_andn2_b32 s9, s9, 63
	s_lshl_b64 s[6:7], s[6:7], 22
	v_ashrrev_i32_e32 v1, 6, v0
	s_waitcnt lgkmcnt(0)
	s_add_u32 s10, s4, s6
	s_addc_u32 s11, s5, s7
	v_add_u32_e32 v2, s9, v1
	s_ashr_i32 s9, s8, 31
	s_lshl_b64 s[6:7], s[8:9], 2
	v_and_b32_e32 v0, 63, v0
	s_add_u32 s6, s10, s6
	s_addc_u32 s7, s11, s7
	v_lshlrev_b32_e32 v10, 2, v0
	s_waitcnt vmcnt(0)
	v_ashrrev_i32_e32 v3, 31, v2
	s_waitcnt vmcnt(13)
	v_lshl_add_u64 v[4:5], s[6:7], 0, v[10:11]
	v_lshlrev_b64 v[2:3], 12, v[2:3]
	s_waitcnt vmcnt(8)
	v_lshl_add_u64 v[12:13], v[4:5], 0, v[2:3]
	v_add_co_u32_e32 v4, vcc, s0, v12
	global_load_dword v2, v[12:13], off
	s_nop 0
	v_addc_co_u32_e32 v5, vcc, 0, v13, vcc
	global_load_dword v3, v[4:5], off
	v_add_co_u32_e32 v4, vcc, s96, v12
	s_load_dwordx2 s[6:7], s[26:27], 0x100
	s_nop 0
	v_addc_co_u32_e32 v5, vcc, 0, v13, vcc
	v_add_co_u32_e32 v6, vcc, s18, v12
	global_load_dword v4, v[4:5], off
	s_nop 0
	v_addc_co_u32_e32 v7, vcc, 0, v13, vcc
	global_load_dword v5, v[6:7], off
	v_add_co_u32_e32 v6, vcc, s19, v12
	v_add_u32_e32 v10, 0, v10
	s_nop 0
	v_addc_co_u32_e32 v7, vcc, 0, v13, vcc
	v_add_co_u32_e32 v8, vcc, s20, v12
	global_load_dword v6, v[6:7], off
	s_nop 0
	v_addc_co_u32_e32 v9, vcc, 0, v13, vcc
	global_load_dword v7, v[8:9], off
	v_add_co_u32_e32 v8, vcc, s21, v12
	s_lshl_b32 s8, s62, 1
	s_nop 0
	v_addc_co_u32_e32 v9, vcc, 0, v13, vcc
	v_add_co_u32_e32 v12, vcc, 0x38000, v12
	global_load_dword v8, v[8:9], off
	s_nop 0
	v_addc_co_u32_e32 v13, vcc, 0, v13, vcc
	global_load_dword v9, v[12:13], off
	v_lshlrev_b32_e32 v12, 8, v0
	v_lshlrev_b32_e32 v13, 2, v1
	v_add3_u32 v12, v10, v12, v13
	v_mul_lo_u32 v13, v1, s22
	s_add_i32 s8, s89, s8
	v_add_u32_e32 v13, v10, v13
	v_lshlrev_b32_e32 v10, 1, v0
	s_mov_b32 s9, s75
	s_waitcnt vmcnt(0)
	s_branch .LBB0_320

; __device__ void transpose_job(const int bid, const int nblk, float* tile, const float* __restrict__ src, bf16_t* __restrict__ dst, int K, int N, int nb, long dstB, float scale) {
;     ...
;     while (t < tot) {
;         const int b = t / per, l = t - b * per, k0 = (l / tn) * 64, n0 = (l % tn) * 64;
;         bf16_t* d = dst + (long)b * dstB;
; #pragma unroll
;         for (int i = 0; i < 8; ++i) tile[(kk + 8 * i) * 65 + nn] = r[i];
;         __syncthreads();
;         const int t2 = t + nblk;
;         if (t2 < tot) { const int b2 = t2 / per, l2 = t2 - b2 * per, k2 = (l2 / tn) * 64, n2 = (l2 % tn) * 64; const float* s2 = src + (long)b2 * K * N;
; #pragma unroll
;             for (int i = 0; i < 8; ++i) r[i] = s2[(long)(k2 + kk + 8 * i) * N + n2 + nn]; }
.LBB0_320:
	s_add_i32 s10, s8, s9
	s_cmpk_gt_i32 s10, 0x1ff
	s_waitcnt vmcnt(15)
	ds_write_b32 v13, v2
	s_waitcnt vmcnt(14)
	ds_write_b32 v13, v3 offset:2080
	s_waitcnt vmcnt(13)
	ds_write_b32 v13, v4 offset:4160
	s_waitcnt vmcnt(12)
	ds_write_b32 v13, v5 offset:6240
	s_waitcnt vmcnt(11)
	ds_write_b32 v13, v6 offset:8320
	s_waitcnt vmcnt(10)
	ds_write_b32 v13, v7 offset:10400
	s_waitcnt vmcnt(9)
	ds_write_b32 v13, v8 offset:12480
	s_waitcnt vmcnt(8)
	ds_write_b32 v13, v9 offset:14560
	s_waitcnt lgkmcnt(0)
	s_barrier
	s_cbranch_scc1 .LBB0_319
	s_ashr_i32 s11, s10, 31
	s_lshr_b32 s11, s11, 24
	s_add_i32 s11, s10, s11
	s_ashr_i32 s12, s11, 8
	s_and_b32 s11, s11, 0xffffff00
	s_sub_i32 s10, s10, s11
	s_ashr_i32 s11, s10, 31
	s_lshr_b32 s11, s11, 28
	s_add_i32 s11, s10, s11
	s_lshl_b32 s13, s11, 2
	s_and_b32 s11, s11, 0x3fffff0
	s_and_b32 s14, s13, 0xffffffc0
	s_sub_i32 s10, s10, s11
	s_ashr_i32 s13, s12, 31
	s_lshl_b32 s10, s10, 6
	s_lshl_b64 s[12:13], s[12:13], 22
	s_add_u32 s12, s4, s12
	s_addc_u32 s13, s5, s13
	s_ashr_i32 s11, s10, 31
	s_lshl_b64 s[10:11], s[10:11], 2
	v_add_u32_e32 v2, s14, v1
	s_add_u32 s10, s12, s10
	s_addc_u32 s11, s13, s11
	v_lshlrev_b32_e32 v4, 2, v0
	v_mov_b32_e32 v5, v11
	v_ashrrev_i32_e32 v3, 31, v2
	v_lshl_add_u64 v[4:5], s[10:11], 0, v[4:5]
	v_lshlrev_b64 v[2:3], 12, v[2:3]
	v_lshl_add_u64 v[14:15], v[4:5], 0, v[2:3]
	v_add_co_u32_e32 v4, vcc, s0, v14
	global_load_dword v2, v[14:15], off
	s_nop 0
	v_addc_co_u32_e32 v5, vcc, 0, v15, vcc
	global_load_dword v3, v[4:5], off
	v_add_co_u32_e32 v4, vcc, s96, v14
	s_nop 1
	v_addc_co_u32_e32 v5, vcc, 0, v15, vcc
	v_add_co_u32_e32 v6, vcc, s18, v14
	global_load_dword v4, v[4:5], off
	s_nop 0
	v_addc_co_u32_e32 v7, vcc, 0, v15, vcc
	global_load_dword v5, v[6:7], off
	v_add_co_u32_e32 v6, vcc, 0x20000, v14
	s_nop 1
	v_addc_co_u32_e32 v7, vcc, 0, v15, vcc
	v_add_co_u32_e32 v8, vcc, 0x28000, v14
	global_load_dword v6, v[6:7], off
	s_nop 0
	v_addc_co_u32_e32 v9, vcc, 0, v15, vcc
	global_load_dword v7, v[8:9], off
	v_add_co_u32_e32 v8, vcc, 0x30000, v14
	s_nop 1
	v_addc_co_u32_e32 v9, vcc, 0, v15, vcc
	v_add_co_u32_e32 v14, vcc, 0x38000, v14
	global_load_dword v8, v[8:9], off
	s_nop 0
	v_addc_co_u32_e32 v15, vcc, 0, v15, vcc
	global_load_dword v9, v[14:15], off
	s_branch .LBB0_319

; __device__ __forceinline__ int tid_() { int t = threadIdx.x; asm volatile("" : "+v"(t)); return t; }
; __device__ void transpose_job(const int bid, const int nblk, float* tile, const float* __restrict__ src, bf16_t* __restrict__ dst, int K, int N, int nb, long dstB, float scale) {
;     const int tk = K / 64, tn = N / 64, per = tk * tn, tot = per * nb, tid = tid_();
;     const int kk = tid >> 6, nn = tid & 63;
;     float r[8];
;     int t = bid;
;     if (t < tot) { const int b = t / per, l = t - b * per, k0 = (l / tn) * 64, n0 = (l % tn) * 64; const float* s = src + (long)b * K * N;
; #pragma unroll
;         for (int i = 0; i < 8; ++i) r[i] = s[(long)(k0 + kk + 8 * i) * N + n0 + nn]; }
.LBB0_323:
	v_mov_b32_e32 v0, v169
	s_cmpk_gt_i32 s8, 0x3ff
	s_cbranch_scc1 .LBB0_328
	v_readlane_b32 s6, v254, 29
	s_mov_b32 s8, s6
	s_ashr_i32 s6, s6, 31
	v_readlane_b32 s7, v254, 30
	s_lshr_b32 s6, s6, 23
	s_add_i32 s7, s8, s6
	s_ashr_i32 s6, s7, 9
	s_and_b32 s7, s7, 0xfffffe00
	s_sub_i32 s7, s8, s7
	s_ashr_i32 s8, s7, 31
	s_lshr_b32 s8, s8, 27
	s_load_dwordx2 s[4:5], s[26:27], 0x98
	s_add_i32 s8, s7, s8
	s_lshl_b32 s9, s8, 1
	s_and_b32 s8, s8, 0x3ffffe0
	s_sub_i32 s7, s7, s8
	s_lshl_b32 s8, s7, 6
	s_ashr_i32 s7, s6, 31
	s_andn2_b32 s9, s9, 63
	s_lshl_b64 s[6:7], s[6:7], 23
	v_ashrrev_i32_e32 v1, 6, v0
	s_waitcnt lgkmcnt(0)
	s_add_u32 s10, s4, s6
	s_addc_u32 s11, s5, s7
	s_waitcnt vmcnt(0)
	v_add_u32_e32 v2, s9, v1
	s_ashr_i32 s9, s8, 31
	s_lshl_b64 s[6:7], s[8:9], 2
	v_and_b32_e32 v0, 63, v0
	s_add_u32 s6, s10, s6
	s_addc_u32 s7, s11, s7
	v_lshlrev_b32_e32 v10, 2, v0
	s_waitcnt vmcnt(14)
	v_ashrrev_i32_e32 v3, 31, v2
	s_waitcnt vmcnt(12)
	v_lshl_add_u64 v[4:5], s[6:7], 0, v[10:11]
	v_lshlrev_b64 v[2:3], 13, v[2:3]
	s_waitcnt vmcnt(8)
	v_lshl_add_u64 v[12:13], v[4:5], 0, v[2:3]
	v_add_co_u32_e32 v4, vcc, s96, v12
	global_load_dword v2, v[12:13], off
	s_nop 0
	v_addc_co_u32_e32 v5, vcc, 0, v13, vcc
	global_load_dword v3, v[4:5], off
	v_add_co_u32_e32 v4, vcc, s19, v12
	s_mov_b32 s6, 0x40000
	s_nop 0
	v_addc_co_u32_e32 v5, vcc, 0, v13, vcc
	v_add_co_u32_e32 v6, vcc, s21, v12
	global_load_dword v4, v[4:5], off
	s_nop 0
	v_addc_co_u32_e32 v7, vcc, 0, v13, vcc
	global_load_dword v5, v[6:7], off
	v_add_co_u32_e32 v6, vcc, s6, v12
	s_mov_b32 s6, 0x50000
	s_nop 0
	v_addc_co_u32_e32 v7, vcc, 0, v13, vcc
	v_add_co_u32_e32 v8, vcc, s6, v12
	s_mov_b32 s6, 0x60000
	s_nop 0
	v_addc_co_u32_e32 v9, vcc, 0, v13, vcc
	global_load_dword v6, v[6:7], off
	v_add_u32_e32 v10, 0, v10
	global_load_dword v7, v[8:9], off
	v_add_co_u32_e32 v8, vcc, s6, v12
	s_load_dwordx2 s[6:7], s[26:27], 0x108
	s_nop 0
	v_addc_co_u32_e32 v9, vcc, 0, v13, vcc
	v_add_co_u32_e32 v12, vcc, 0x70000, v12
	global_load_dword v8, v[8:9], off
	s_nop 0
	v_addc_co_u32_e32 v13, vcc, 0, v13, vcc
	global_load_dword v9, v[12:13], off
	v_lshlrev_b32_e32 v12, 8, v0
	v_lshlrev_b32_e32 v13, 2, v1
	v_add3_u32 v12, v10, v12, v13
	v_mul_lo_u32 v13, v1, s22
	s_lshl_b32 s8, s62, 1
	s_add_i32 s8, s89, s8
	v_add_u32_e32 v13, v10, v13
	v_lshlrev_b32_e32 v10, 1, v0
	s_mov_b32 s9, s75
	s_waitcnt vmcnt(0)
	s_branch .LBB0_326

; __device__ __forceinline__ int tid_() { int t = threadIdx.x; asm volatile("" : "+v"(t)); return t; }
; __device__ void transpose_job(const int bid, const int nblk, float* tile, const float* __restrict__ src, bf16_t* __restrict__ dst, int K, int N, int nb, long dstB, float scale) {
;     const int tk = K / 64, tn = N / 64, per = tk * tn, tot = per * nb, tid = tid_();
;     const int kk = tid >> 6, nn = tid & 63;
;     float r[8];
;     int t = bid;
;     if (t < tot) { const int b = t / per, l = t - b * per, k0 = (l / tn) * 64, n0 = (l % tn) * 64; const float* s = src + (long)b * K * N;
; #pragma unroll
;         for (int i = 0; i < 8; ++i) r[i] = s[(long)(k0 + kk + 8 * i) * N + n0 + nn]; }
;     while (t < tot) {
;         const int b = t / per, l = t - b * per, k0 = (l / tn) * 64, n0 = (l % tn) * 64;
;         bf16_t* d = dst + (long)b * dstB;
; #pragma unroll
;         for (int i = 0; i < 8; ++i) tile[(kk + 8 * i) * 65 + nn] = r[i];
;         __syncthreads();
;         const int t2 = t + nblk;
;         if (t2 < tot) { const int b2 = t2 / per, l2 = t2 - b2 * per, k2 = (l2 / tn) * 64, n2 = (l2 % tn) * 64; const float* s2 = src + (long)b2 * K * N;
; #pragma unroll
;             for (int i = 0; i < 8; ++i) r[i] = s2[(long)(k2 + kk + 8 * i) * N + n2 + nn]; }
.LBB0_326:
	s_add_i32 s10, s8, s9
	s_cmpk_gt_i32 s10, 0x3ff
	s_waitcnt vmcnt(15)
	ds_write_b32 v13, v2
	s_waitcnt vmcnt(14)
	ds_write_b32 v13, v3 offset:2080
	s_waitcnt vmcnt(13)
	ds_write_b32 v13, v4 offset:4160
	s_waitcnt vmcnt(12)
	ds_write_b32 v13, v5 offset:6240
	s_waitcnt vmcnt(11)
	ds_write_b32 v13, v6 offset:8320
	s_waitcnt vmcnt(10)
	ds_write_b32 v13, v7 offset:10400
	s_waitcnt vmcnt(9)
	ds_write_b32 v13, v8 offset:12480
	s_waitcnt vmcnt(8)
	ds_write_b32 v13, v9 offset:14560
	s_waitcnt lgkmcnt(0)
	s_barrier
	s_cbranch_scc1 .LBB0_325
	s_ashr_i32 s11, s10, 31
	s_lshr_b32 s11, s11, 23
	s_add_i32 s11, s10, s11
	s_ashr_i32 s12, s11, 9
	s_and_b32 s11, s11, 0xfffffe00
	s_sub_i32 s10, s10, s11
	s_ashr_i32 s11, s10, 31
	s_lshr_b32 s11, s11, 27
	s_add_i32 s11, s10, s11
	s_lshl_b32 s13, s11, 1
	s_and_b32 s11, s11, 0x3ffffe0
	s_and_b32 s14, s13, 0xffffffc0
	s_sub_i32 s10, s10, s11
	s_ashr_i32 s13, s12, 31
	s_lshl_b32 s10, s10, 6
	s_lshl_b64 s[12:13], s[12:13], 23
	s_add_u32 s12, s4, s12
	s_addc_u32 s13, s5, s13
	s_ashr_i32 s11, s10, 31
	s_lshl_b64 s[10:11], s[10:11], 2
	v_add_u32_e32 v2, s14, v1
	s_add_u32 s10, s12, s10
	s_addc_u32 s11, s13, s11
	v_lshlrev_b32_e32 v4, 2, v0
	v_mov_b32_e32 v5, v11
	v_ashrrev_i32_e32 v3, 31, v2
	v_lshl_add_u64 v[4:5], s[10:11], 0, v[4:5]
	v_lshlrev_b64 v[2:3], 13, v[2:3]
	v_lshl_add_u64 v[14:15], v[4:5], 0, v[2:3]
	v_add_co_u32_e32 v4, vcc, s96, v14
	global_load_dword v2, v[14:15], off
	s_nop 0
	v_addc_co_u32_e32 v5, vcc, 0, v15, vcc
	global_load_dword v3, v[4:5], off
	v_add_co_u32_e32 v4, vcc, s19, v14
	s_nop 1
	v_addc_co_u32_e32 v5, vcc, 0, v15, vcc
	v_add_co_u32_e32 v6, vcc, s21, v14
	global_load_dword v4, v[4:5], off
	s_nop 0
	v_addc_co_u32_e32 v7, vcc, 0, v15, vcc
	global_load_dword v5, v[6:7], off
	v_add_co_u32_e32 v6, vcc, 0x40000, v14
	s_nop 1
	v_addc_co_u32_e32 v7, vcc, 0, v15, vcc
	v_add_co_u32_e32 v8, vcc, 0x50000, v14
	global_load_dword v6, v[6:7], off
	s_nop 0
	v_addc_co_u32_e32 v9, vcc, 0, v15, vcc
	global_load_dword v7, v[8:9], off
	v_add_co_u32_e32 v8, vcc, 0x60000, v14
	s_nop 1
	v_addc_co_u32_e32 v9, vcc, 0, v15, vcc
	v_add_co_u32_e32 v14, vcc, 0x70000, v14
	global_load_dword v8, v[8:9], off
	s_nop 0
	v_addc_co_u32_e32 v15, vcc, 0, v15, vcc
	global_load_dword v9, v[14:15], off
	s_branch .LBB0_325
.LBB0_328:
	v_mov_b32_e32 v0, v169
	s_andn2_b64 vcc, exec, s[2:3]
	s_cbranch_vccnz .LBB0_333
	v_readlane_b32 s4, v254, 29
	s_mov_b32 s6, s4
	s_ashr_i32 s4, s4, 31
	v_readlane_b32 s5, v254, 30
	s_lshr_b32 s4, s4, 24
	s_add_i32 s5, s6, s4
	s_ashr_i32 s4, s5, 8
	s_and_b32 s5, s5, 0xffffff00
	s_sub_i32 s5, s6, s5
	s_ashr_i32 s6, s5, 31
	s_lshr_b32 s6, s6, 28
	s_load_dwordx2 s[2:3], s[26:27], 0xa0
	s_add_i32 s6, s5, s6
	s_lshl_b32 s7, s6, 2
	s_and_b32 s6, s6, 0x3fffff0
	s_sub_i32 s5, s5, s6
	s_lshl_b32 s6, s5, 6
	s_ashr_i32 s5, s4, 31
	s_andn2_b32 s7, s7, 63
	s_lshl_b64 s[4:5], s[4:5], 22
	v_ashrrev_i32_e32 v1, 6, v0
	s_waitcnt lgkmcnt(0)
	s_add_u32 s8, s2, s4
	s_addc_u32 s9, s3, s5
	s_waitcnt vmcnt(0)
	v_add_u32_e32 v2, s7, v1
	s_ashr_i32 s7, s6, 31
	s_lshl_b64 s[4:5], s[6:7], 2
	v_and_b32_e32 v0, 63, v0
	s_add_u32 s4, s8, s4
	s_addc_u32 s5, s9, s5
	v_lshlrev_b32_e32 v10, 2, v0
	s_waitcnt vmcnt(14)
	v_ashrrev_i32_e32 v3, 31, v2
	s_waitcnt vmcnt(12)
	v_lshl_add_u64 v[4:5], s[4:5], 0, v[10:11]
	v_lshlrev_b64 v[2:3], 12, v[2:3]
	s_waitcnt vmcnt(8)
	v_lshl_add_u64 v[12:13], v[4:5], 0, v[2:3]
	v_add_co_u32_e32 v4, vcc, s0, v12
	global_load_dword v2, v[12:13], off
	s_nop 0
	v_addc_co_u32_e32 v5, vcc, 0, v13, vcc
	global_load_dword v3, v[4:5], off
	v_add_co_u32_e32 v4, vcc, s96, v12
	s_load_dwordx2 s[4:5], s[26:27], 0x110
	s_nop 0
	v_addc_co_u32_e32 v5, vcc, 0, v13, vcc
	v_add_co_u32_e32 v6, vcc, s18, v12
	global_load_dword v4, v[4:5], off
	s_nop 0
	v_addc_co_u32_e32 v7, vcc, 0, v13, vcc
	global_load_dword v5, v[6:7], off
	v_add_co_u32_e32 v6, vcc, s19, v12
	v_add_u32_e32 v10, 0, v10
	s_nop 0
	v_addc_co_u32_e32 v7, vcc, 0, v13, vcc
	v_add_co_u32_e32 v8, vcc, s20, v12
	global_load_dword v6, v[6:7], off
	s_nop 0
	v_addc_co_u32_e32 v9, vcc, 0, v13, vcc
	global_load_dword v7, v[8:9], off
	v_add_co_u32_e32 v8, vcc, s21, v12
	s_lshl_b32 s6, s62, 1
	s_nop 0
	v_addc_co_u32_e32 v9, vcc, 0, v13, vcc
	v_add_co_u32_e32 v12, vcc, 0x38000, v12
	global_load_dword v8, v[8:9], off
	s_nop 0
	v_addc_co_u32_e32 v13, vcc, 0, v13, vcc
	global_load_dword v9, v[12:13], off
	v_lshlrev_b32_e32 v12, 8, v0
	v_lshlrev_b32_e32 v13, 2, v1
	v_add3_u32 v12, v10, v12, v13
	v_mul_lo_u32 v13, v1, s22
	s_add_i32 s6, s89, s6
	v_add_u32_e32 v13, v10, v13
	v_lshlrev_b32_e32 v10, 1, v0
	s_mov_b32 s7, s75
	s_waitcnt vmcnt(0)
	s_branch .LBB0_331

; __device__ __forceinline__ int tid_() { int t = threadIdx.x; asm volatile("" : "+v"(t)); return t; }
; __device__ void transpose_job(const int bid, const int nblk, float* tile, const float* __restrict__ src, bf16_t* __restrict__ dst, int K, int N, int nb, long dstB, float scale) {
;     const int tk = K / 64, tn = N / 64, per = tk * tn, tot = per * nb, tid = tid_();
;     const int kk = tid >> 6, nn = tid & 63;
;     float r[8];
;     int t = bid;
;     if (t < tot) { const int b = t / per, l = t - b * per, k0 = (l / tn) * 64, n0 = (l % tn) * 64; const float* s = src + (long)b * K * N;
; #pragma unroll
;         for (int i = 0; i < 8; ++i) r[i] = s[(long)(k0 + kk + 8 * i) * N + n0 + nn]; }
;     while (t < tot) {
;         const int b = t / per, l = t - b * per, k0 = (l / tn) * 64, n0 = (l % tn) * 64;
;         bf16_t* d = dst + (long)b * dstB;
; #pragma unroll
;         for (int i = 0; i < 8; ++i) tile[(kk + 8 * i) * 65 + nn] = r[i];
;         __syncthreads();
;         const int t2 = t + nblk;
;         if (t2 < tot) { const int b2 = t2 / per, l2 = t2 - b2 * per, k2 = (l2 / tn) * 64, n2 = (l2 % tn) * 64; const float* s2 = src + (long)b2 * K * N;
; #pragma unroll
;             for (int i = 0; i < 8; ++i) r[i] = s2[(long)(k2 + kk + 8 * i) * N + n2 + nn]; }
.LBB0_331:
	s_add_i32 s8, s6, s7
	s_cmpk_gt_i32 s8, 0x1ff
	s_waitcnt vmcnt(15)
	ds_write_b32 v13, v2
	s_waitcnt vmcnt(14)
	ds_write_b32 v13, v3 offset:2080
	s_waitcnt vmcnt(13)
	ds_write_b32 v13, v4 offset:4160
	s_waitcnt vmcnt(12)
	ds_write_b32 v13, v5 offset:6240
	s_waitcnt vmcnt(11)
	ds_write_b32 v13, v6 offset:8320
	s_waitcnt vmcnt(10)
	ds_write_b32 v13, v7 offset:10400
	s_waitcnt vmcnt(9)
	ds_write_b32 v13, v8 offset:12480
	s_waitcnt vmcnt(8)
	ds_write_b32 v13, v9 offset:14560
	s_waitcnt lgkmcnt(0)
	s_barrier
	s_cbranch_scc1 .LBB0_330
	s_ashr_i32 s9, s8, 31
	s_lshr_b32 s9, s9, 24
	s_add_i32 s9, s8, s9
	s_ashr_i32 s10, s9, 8
	s_and_b32 s9, s9, 0xffffff00
	s_sub_i32 s8, s8, s9
	s_ashr_i32 s9, s8, 31
	s_lshr_b32 s9, s9, 28
	s_add_i32 s9, s8, s9
	s_lshl_b32 s11, s9, 2
	s_and_b32 s9, s9, 0x3fffff0
	s_and_b32 s12, s11, 0xffffffc0
	s_sub_i32 s8, s8, s9
	s_ashr_i32 s11, s10, 31
	s_lshl_b32 s8, s8, 6
	s_lshl_b64 s[10:11], s[10:11], 22
	s_add_u32 s10, s2, s10
	s_addc_u32 s11, s3, s11
	s_ashr_i32 s9, s8, 31
	s_lshl_b64 s[8:9], s[8:9], 2
	v_add_u32_e32 v2, s12, v1
	s_add_u32 s8, s10, s8
	s_addc_u32 s9, s11, s9
	v_lshlrev_b32_e32 v4, 2, v0
	v_mov_b32_e32 v5, v11
	v_ashrrev_i32_e32 v3, 31, v2
	v_lshl_add_u64 v[4:5], s[8:9], 0, v[4:5]
	v_lshlrev_b64 v[2:3], 12, v[2:3]
	v_lshl_add_u64 v[14:15], v[4:5], 0, v[2:3]
	v_add_co_u32_e32 v4, vcc, s0, v14
	global_load_dword v2, v[14:15], off
	s_nop 0
	v_addc_co_u32_e32 v5, vcc, 0, v15, vcc
	global_load_dword v3, v[4:5], off
	v_add_co_u32_e32 v4, vcc, s96, v14
	s_nop 1
	v_addc_co_u32_e32 v5, vcc, 0, v15, vcc
	v_add_co_u32_e32 v6, vcc, s18, v14
	global_load_dword v4, v[4:5], off
	s_nop 0
	v_addc_co_u32_e32 v7, vcc, 0, v15, vcc
	global_load_dword v5, v[6:7], off
	v_add_co_u32_e32 v6, vcc, 0x20000, v14
	s_nop 1
	v_addc_co_u32_e32 v7, vcc, 0, v15, vcc
	v_add_co_u32_e32 v8, vcc, 0x28000, v14
	global_load_dword v6, v[6:7], off
	s_nop 0
	v_addc_co_u32_e32 v9, vcc, 0, v15, vcc
	global_load_dword v7, v[8:9], off
	v_add_co_u32_e32 v8, vcc, 0x30000, v14
	s_nop 1
	v_addc_co_u32_e32 v9, vcc, 0, v15, vcc
	v_add_co_u32_e32 v14, vcc, 0x38000, v14
	global_load_dword v8, v[8:9], off
	s_nop 0
	v_addc_co_u32_e32 v15, vcc, 0, v15, vcc
	global_load_dword v9, v[14:15], off
	s_branch .LBB0_330
.LBB0_333:
	v_readlane_b32 s8, v254, 29
	v_mov_b32_e32 v0, v169
	s_cmpk_gt_i32 s8, 0xaff
	s_mul_hi_i32 s6, s8, 0x2e8ba2e9
	v_readlane_b32 s9, v254, 30
	s_cbranch_scc1 .LBB0_339
	s_lshr_b32 s4, s6, 31
	s_ashr_i32 s5, s6, 8
	s_add_i32 s5, s5, s4
	s_mul_i32 s4, s5, 0xfffffa80
	s_add_i32 s4, s4, s8
	s_mul_hi_i32 s7, s4, 0x2e8ba2e9
	s_load_dwordx2 s[2:3], s[26:27], 0xb0
	s_lshr_b32 s8, s7, 31
	s_ashr_i32 s7, s7, 4
	s_add_i32 s7, s7, s8
	s_mul_i32 s8, s7, 0x58
	s_sub_i32 s4, s4, s8
	s_lshl_b32 s4, s4, 6
	s_mul_hi_i32 s8, s5, 0x1600000
	s_mul_i32 s5, s5, 0x1600000
	s_waitcnt lgkmcnt(0)
	s_add_u32 s9, s2, s5
	s_addc_u32 s8, s3, s8
	s_ashr_i32 s5, s4, 31
	s_lshl_b64 s[4:5], s[4:5], 2
	v_ashrrev_i32_e32 v1, 6, v0
	v_and_b32_e32 v0, 63, v0
	s_add_u32 s4, s9, s4
	s_addc_u32 s5, s8, s5
	v_lshlrev_b32_e32 v10, 2, v0
	v_lshl_add_u32 v14, s7, 6, v1
	s_waitcnt vmcnt(0)
	v_lshl_add_u64 v[12:13], s[4:5], 0, v[10:11]
	v_mad_i64_i32 v[2:3], s[4:5], v14, s17, v[12:13]
	global_load_dword v2, v[2:3], off
	v_add_u32_e32 v3, 8, v14
	v_mad_i64_i32 v[4:5], s[4:5], v3, s17, v[12:13]
	global_load_dword v3, v[4:5], off
	v_add_u32_e32 v4, 16, v14
	v_mad_i64_i32 v[4:5], s[4:5], v4, s17, v[12:13]
	global_load_dword v4, v[4:5], off
	v_add_u32_e32 v5, 24, v14
	v_mad_i64_i32 v[6:7], s[4:5], v5, s17, v[12:13]
	global_load_dword v5, v[6:7], off
	v_add_u32_e32 v6, 32, v14
	v_mad_i64_i32 v[6:7], s[4:5], v6, s17, v[12:13]
	global_load_dword v6, v[6:7], off
	v_add_u32_e32 v7, 40, v14
	v_mad_i64_i32 v[8:9], s[4:5], v7, s17, v[12:13]
	global_load_dword v7, v[8:9], off
	v_add_u32_e32 v8, 48, v14
	v_mad_i64_i32 v[8:9], s[4:5], v8, s17, v[12:13]
	global_load_dword v8, v[8:9], off
	v_add_u32_e32 v9, 56, v14
	v_mad_i64_i32 v[12:13], s[4:5], v9, s17, v[12:13]
	global_load_dword v9, v[12:13], off
	s_load_dwordx2 s[4:5], s[26:27], 0x118
	v_add_u32_e32 v10, 0, v10
	v_lshlrev_b32_e32 v12, 8, v0
	v_lshlrev_b32_e32 v13, 2, v1
	v_add3_u32 v12, v10, v12, v13
	v_mul_lo_u32 v13, v1, s22
	s_lshl_b32 s7, s62, 1
	s_add_i32 s7, s89, s7
	v_add_u32_e32 v13, v10, v13
	v_lshlrev_b32_e32 v10, 1, v0
	s_mov_b32 s8, s75
	s_waitcnt vmcnt(0)
	s_branch .LBB0_336

; __device__ void transpose_job(const int bid, const int nblk, float* tile, const float* __restrict__ src, bf16_t* __restrict__ dst, int K, int N, int nb, long dstB, float scale) {
;     ...
;     while (t < tot) {
;         const int b = t / per, l = t - b * per, k0 = (l / tn) * 64, n0 = (l % tn) * 64;
;         bf16_t* d = dst + (long)b * dstB;
; #pragma unroll
;         for (int i = 0; i < 8; ++i) tile[(kk + 8 * i) * 65 + nn] = r[i];
;         __syncthreads();
;         const int t2 = t + nblk;
;         if (t2 < tot) { const int b2 = t2 / per, l2 = t2 - b2 * per, k2 = (l2 / tn) * 64, n2 = (l2 % tn) * 64; const float* s2 = src + (long)b2 * K * N;
; #pragma unroll
;             for (int i = 0; i < 8; ++i) r[i] = s2[(long)(k2 + kk + 8 * i) * N + n2 + nn]; }
.LBB0_336:
	s_add_i32 s9, s7, s8
	s_cmpk_gt_i32 s9, 0xaff
	s_waitcnt vmcnt(15)
	ds_write_b32 v13, v2
	s_waitcnt vmcnt(14)
	ds_write_b32 v13, v3 offset:2080
	s_waitcnt vmcnt(13)
	ds_write_b32 v13, v4 offset:4160
	s_waitcnt vmcnt(12)
	ds_write_b32 v13, v5 offset:6240
	s_waitcnt vmcnt(11)
	ds_write_b32 v13, v6 offset:8320
	s_waitcnt vmcnt(10)
	ds_write_b32 v13, v7 offset:10400
	s_waitcnt vmcnt(9)
	ds_write_b32 v13, v8 offset:12480
	s_waitcnt vmcnt(8)
	ds_write_b32 v13, v9 offset:14560
	s_waitcnt lgkmcnt(0)
	s_barrier
	s_cbranch_scc1 .LBB0_335
	s_mul_hi_i32 s10, s9, 0x2e8ba2e9
	s_lshr_b32 s11, s10, 31
	s_ashr_i32 s10, s10, 8
	s_add_i32 s11, s10, s11
	s_mul_i32 s10, s11, 0xfffffa80
	s_add_i32 s9, s9, s10
	s_mul_hi_i32 s10, s9, 0x2e8ba2e9
	s_lshr_b32 s12, s10, 31
	s_ashr_i32 s10, s10, 4
	s_add_i32 s12, s10, s12
	s_mul_i32 s10, s12, 0x58
	s_sub_i32 s9, s9, s10
	s_lshl_b32 s10, s9, 6
	s_mul_hi_i32 s9, s11, 0x1600000
	s_mul_i32 s11, s11, 0x1600000
	s_add_u32 s13, s2, s11
	s_addc_u32 s9, s3, s9
	s_ashr_i32 s11, s10, 31
	s_lshl_b64 s[10:11], s[10:11], 2
	s_add_u32 s10, s13, s10
	s_addc_u32 s11, s9, s11
	v_lshlrev_b32_e32 v2, 2, v0
	v_mov_b32_e32 v3, v11
	v_lshl_add_u32 v16, s12, 6, v1
	v_lshl_add_u64 v[14:15], s[10:11], 0, v[2:3]
	v_mad_i64_i32 v[2:3], s[10:11], v16, s17, v[14:15]
	global_load_dword v2, v[2:3], off
	v_add_u32_e32 v3, 8, v16
	v_mad_i64_i32 v[4:5], s[10:11], v3, s17, v[14:15]
	global_load_dword v3, v[4:5], off
	v_add_u32_e32 v4, 16, v16
	v_mad_i64_i32 v[4:5], s[10:11], v4, s17, v[14:15]
	global_load_dword v4, v[4:5], off
	v_add_u32_e32 v5, 24, v16
	v_mad_i64_i32 v[6:7], s[10:11], v5, s17, v[14:15]
	global_load_dword v5, v[6:7], off
	v_add_u32_e32 v6, 32, v16
	v_mad_i64_i32 v[6:7], s[10:11], v6, s17, v[14:15]
	global_load_dword v6, v[6:7], off
	v_add_u32_e32 v7, 40, v16
	v_mad_i64_i32 v[8:9], s[10:11], v7, s17, v[14:15]
	global_load_dword v7, v[8:9], off
	v_add_u32_e32 v8, 48, v16
	v_mad_i64_i32 v[8:9], s[10:11], v8, s17, v[14:15]
	global_load_dword v8, v[8:9], off
	v_add_u32_e32 v9, 56, v16
	v_mad_i64_i32 v[14:15], s[10:11], v9, s17, v[14:15]
	global_load_dword v9, v[14:15], off
	s_branch .LBB0_335

; __device__ __forceinline__ int tid_() { int t = threadIdx.x; asm volatile("" : "+v"(t)); return t; }
; __device__ void transpose_job(const int bid, const int nblk, float* tile, const float* __restrict__ src, bf16_t* __restrict__ dst, int K, int N, int nb, long dstB, float scale) {
;     const int tk = K / 64, tn = N / 64, per = tk * tn, tot = per * nb, tid = tid_();
;     const int kk = tid >> 6, nn = tid & 63;
;     float r[8];
;     int t = bid;
;     if (t < tot) { const int b = t / per, l = t - b * per, k0 = (l / tn) * 64, n0 = (l % tn) * 64; const float* s = src + (long)b * K * N;
; #pragma unroll
;         for (int i = 0; i < 8; ++i) r[i] = s[(long)(k0 + kk + 8 * i) * N + n0 + nn]; }
.LBB0_339:
	v_mov_b32_e32 v0, v169
	s_cmpk_gt_i32 s8, 0x57f
	s_cbranch_scc1 .LBB0_345
	s_lshr_b32 s4, s6, 31
	s_ashr_i32 s5, s6, 7
	s_add_i32 s5, s5, s4
	s_mul_i32 s4, s5, 0xfffffd40
	s_add_i32 s4, s4, s8
	s_ashr_i32 s6, s4, 31
	s_load_dwordx2 s[2:3], s[26:27], 0xc8
	s_lshr_b32 s6, s6, 28
	s_add_i32 s6, s4, s6
	s_lshl_b32 s7, s6, 2
	s_and_b32 s6, s6, 0x3fffff0
	s_sub_i32 s4, s4, s6
	s_andn2_b32 s7, s7, 63
	s_lshl_b32 s4, s4, 6
	s_mul_hi_i32 s6, s5, 0xb00000
	s_mul_i32 s5, s5, 0xb00000
	s_waitcnt lgkmcnt(0)
	s_add_u32 s8, s2, s5
	s_addc_u32 s6, s3, s6
	s_ashr_i32 s5, s4, 31
	v_ashrrev_i32_e32 v1, 6, v0
	s_lshl_b64 s[4:5], s[4:5], 2
	v_and_b32_e32 v0, 63, v0
	s_waitcnt vmcnt(0)
	v_add_u32_e32 v2, s7, v1
	s_add_u32 s4, s8, s4
	s_addc_u32 s5, s6, s5
	v_lshlrev_b32_e32 v10, 2, v0
	s_waitcnt vmcnt(14)
	v_ashrrev_i32_e32 v3, 31, v2
	s_waitcnt vmcnt(12)
	v_lshl_add_u64 v[4:5], s[4:5], 0, v[10:11]
	v_lshlrev_b64 v[2:3], 12, v[2:3]
	s_waitcnt vmcnt(8)
	v_lshl_add_u64 v[12:13], v[4:5], 0, v[2:3]
	v_add_co_u32_e32 v4, vcc, s0, v12
	global_load_dword v2, v[12:13], off
	s_nop 0
	v_addc_co_u32_e32 v5, vcc, 0, v13, vcc
	global_load_dword v3, v[4:5], off
	v_add_co_u32_e32 v4, vcc, s96, v12
	s_load_dwordx2 s[4:5], s[26:27], 0x120
	s_nop 0
	v_addc_co_u32_e32 v5, vcc, 0, v13, vcc
	v_add_co_u32_e32 v6, vcc, s18, v12
	global_load_dword v4, v[4:5], off
	s_nop 0
	v_addc_co_u32_e32 v7, vcc, 0, v13, vcc
	global_load_dword v5, v[6:7], off
	v_add_co_u32_e32 v6, vcc, s19, v12
	v_add_u32_e32 v10, 0, v10
	s_nop 0
	v_addc_co_u32_e32 v7, vcc, 0, v13, vcc
	v_add_co_u32_e32 v8, vcc, s20, v12
	global_load_dword v6, v[6:7], off
	s_nop 0
	v_addc_co_u32_e32 v9, vcc, 0, v13, vcc
	global_load_dword v7, v[8:9], off
	v_add_co_u32_e32 v8, vcc, s21, v12
	s_lshl_b32 s6, s62, 1
	s_nop 0
	v_addc_co_u32_e32 v9, vcc, 0, v13, vcc
	v_add_co_u32_e32 v12, vcc, 0x38000, v12
	global_load_dword v8, v[8:9], off
	s_nop 0
	v_addc_co_u32_e32 v13, vcc, 0, v13, vcc
	global_load_dword v9, v[12:13], off
	v_lshlrev_b32_e32 v12, 8, v0
	v_lshlrev_b32_e32 v13, 2, v1
	v_add3_u32 v12, v10, v12, v13
	v_mul_lo_u32 v13, v1, s22
	s_add_i32 s6, s89, s6
	v_add_u32_e32 v13, v10, v13
	v_lshlrev_b32_e32 v10, 1, v0
	s_mov_b32 s7, s75
	s_waitcnt vmcnt(0)
	s_branch .LBB0_342

; __device__ void transpose_job(const int bid, const int nblk, float* tile, const float* __restrict__ src, bf16_t* __restrict__ dst, int K, int N, int nb, long dstB, float scale) {
;     ...
;     while (t < tot) {
;         const int b = t / per, l = t - b * per, k0 = (l / tn) * 64, n0 = (l % tn) * 64;
;         bf16_t* d = dst + (long)b * dstB;
; #pragma unroll
;         for (int i = 0; i < 8; ++i) tile[(kk + 8 * i) * 65 + nn] = r[i];
;         __syncthreads();
;         const int t2 = t + nblk;
;         if (t2 < tot) { const int b2 = t2 / per, l2 = t2 - b2 * per, k2 = (l2 / tn) * 64, n2 = (l2 % tn) * 64; const float* s2 = src + (long)b2 * K * N;
; #pragma unroll
;             for (int i = 0; i < 8; ++i) r[i] = s2[(long)(k2 + kk + 8 * i) * N + n2 + nn]; }
.LBB0_342:
	s_add_i32 s8, s6, s7
	s_cmpk_gt_i32 s8, 0x57f
	s_waitcnt vmcnt(15)
	ds_write_b32 v13, v2
	s_waitcnt vmcnt(14)
	ds_write_b32 v13, v3 offset:2080
	s_waitcnt vmcnt(13)
	ds_write_b32 v13, v4 offset:4160
	s_waitcnt vmcnt(12)
	ds_write_b32 v13, v5 offset:6240
	s_waitcnt vmcnt(11)
	ds_write_b32 v13, v6 offset:8320
	s_waitcnt vmcnt(10)
	ds_write_b32 v13, v7 offset:10400
	s_waitcnt vmcnt(9)
	ds_write_b32 v13, v8 offset:12480
	s_waitcnt vmcnt(8)
	ds_write_b32 v13, v9 offset:14560
	s_waitcnt lgkmcnt(0)
	s_barrier
	s_cbranch_scc1 .LBB0_341
	s_mul_hi_i32 s9, s8, 0x2e8ba2e9
	s_lshr_b32 s10, s9, 31
	s_ashr_i32 s9, s9, 7
	s_add_i32 s9, s9, s10
	s_mul_i32 s10, s9, 0xfffffd40
	s_add_i32 s8, s8, s10
	s_ashr_i32 s10, s8, 31
	s_lshr_b32 s10, s10, 28
	s_add_i32 s10, s8, s10
	s_lshl_b32 s11, s10, 2
	s_and_b32 s10, s10, 0x3fffff0
	s_sub_i32 s8, s8, s10
	s_andn2_b32 s11, s11, 63
	s_lshl_b32 s8, s8, 6
	s_mul_hi_i32 s10, s9, 0xb00000
	s_mul_i32 s9, s9, 0xb00000
	s_add_u32 s12, s2, s9
	s_addc_u32 s10, s3, s10
	s_ashr_i32 s9, s8, 31
	s_lshl_b64 s[8:9], s[8:9], 2
	v_add_u32_e32 v2, s11, v1
	s_add_u32 s8, s12, s8
	s_addc_u32 s9, s10, s9
	v_lshlrev_b32_e32 v4, 2, v0
	v_mov_b32_e32 v5, v11
	v_ashrrev_i32_e32 v3, 31, v2
	v_lshl_add_u64 v[4:5], s[8:9], 0, v[4:5]
	v_lshlrev_b64 v[2:3], 12, v[2:3]
	v_lshl_add_u64 v[14:15], v[4:5], 0, v[2:3]
	v_add_co_u32_e32 v4, vcc, s0, v14
	global_load_dword v2, v[14:15], off
	s_nop 0
	v_addc_co_u32_e32 v5, vcc, 0, v15, vcc
	global_load_dword v3, v[4:5], off
	v_add_co_u32_e32 v4, vcc, s96, v14
	s_nop 1
	v_addc_co_u32_e32 v5, vcc, 0, v15, vcc
	v_add_co_u32_e32 v6, vcc, s18, v14
	global_load_dword v4, v[4:5], off
	s_nop 0
	v_addc_co_u32_e32 v7, vcc, 0, v15, vcc
	global_load_dword v5, v[6:7], off
	v_add_co_u32_e32 v6, vcc, 0x20000, v14
	s_nop 1
	v_addc_co_u32_e32 v7, vcc, 0, v15, vcc
	v_add_co_u32_e32 v8, vcc, 0x28000, v14
	global_load_dword v6, v[6:7], off
	s_nop 0
	v_addc_co_u32_e32 v9, vcc, 0, v15, vcc
	global_load_dword v7, v[8:9], off
	v_add_co_u32_e32 v8, vcc, 0x30000, v14
	s_nop 1
	v_addc_co_u32_e32 v9, vcc, 0, v15, vcc
	v_add_co_u32_e32 v14, vcc, 0x38000, v14
	global_load_dword v8, v[8:9], off
	s_nop 0
	v_addc_co_u32_e32 v15, vcc, 0, v15, vcc
	global_load_dword v9, v[14:15], off
	s_branch .LBB0_341

; __device__ __forceinline__ int tid_() { int t = threadIdx.x; asm volatile("" : "+v"(t)); return t; }
; __device__ void transpose_job(const int bid, const int nblk, float* tile, const float* __restrict__ src, bf16_t* __restrict__ dst, int K, int N, int nb, long dstB, float scale) {
;     const int tk = K / 64, tn = N / 64, per = tk * tn, tot = per * nb, tid = tid_();
;     const int kk = tid >> 6, nn = tid & 63;
;     float r[8];
;     int t = bid;
;     if (t < tot) { const int b = t / per, l = t - b * per, k0 = (l / tn) * 64, n0 = (l % tn) * 64; const float* s = src + (long)b * K * N;
; #pragma unroll
;         for (int i = 0; i < 8; ++i) r[i] = s[(long)(k0 + kk + 8 * i) * N + n0 + nn]; }
.LBB0_345:
	s_load_dwordx2 s[2:3], s[26:27], 0xf0
	s_cmpk_lt_i32 s8, 0x50
	v_mov_b32_e32 v0, v169
	s_cselect_b64 s[4:5], -1, 0
	s_cmpk_gt_i32 s8, 0x4f
	s_cbranch_scc1 .LBB0_351
	v_readlane_b32 s8, v254, 29
	s_mov_b32 s10, s8
	s_ashr_i32 s8, s8, 31
	v_readlane_b32 s9, v254, 30
	s_lshr_b32 s8, s8, 30
	s_add_i32 s9, s10, s8
	s_ashr_i32 s8, s9, 2
	s_and_b32 s9, s9, -4
	s_sub_i32 s9, s10, s9
	s_lshr_b32 s10, s9, 31
	s_load_dwordx2 s[6:7], s[26:27], 0x50
	s_add_i32 s10, s9, s10
	s_lshl_b32 s11, s10, 5
	s_and_b32 s10, s10, 0x3fffffe
	s_sub_i32 s9, s9, s10
	s_lshl_b32 s10, s9, 6
	s_ashr_i32 s9, s8, 31
	s_andn2_b32 s11, s11, 63
	s_lshl_b64 s[8:9], s[8:9], 16
	v_ashrrev_i32_e32 v1, 6, v0
	s_waitcnt lgkmcnt(0)
	s_add_u32 s12, s6, s8
	s_addc_u32 s13, s7, s9
	s_waitcnt vmcnt(0)
	v_add_u32_e32 v2, s11, v1
	s_ashr_i32 s11, s10, 31
	s_lshl_b64 s[8:9], s[10:11], 2
	v_and_b32_e32 v0, 63, v0
	s_add_u32 s8, s12, s8
	s_addc_u32 s9, s13, s9
	v_lshlrev_b32_e32 v10, 2, v0
	s_waitcnt vmcnt(14)
	v_ashrrev_i32_e32 v3, 31, v2
	s_waitcnt vmcnt(12)
	v_lshl_add_u64 v[4:5], s[8:9], 0, v[10:11]
	v_lshlrev_b64 v[2:3], 9, v[2:3]
	s_waitcnt vmcnt(10)
	v_lshl_add_u64 v[6:7], v[4:5], 0, v[2:3]
	v_add_co_u32_e32 v4, vcc, s76, v6
	global_load_dword v2, v[6:7], off
	s_nop 0
	v_addc_co_u32_e32 v5, vcc, 0, v7, vcc
	s_waitcnt vmcnt(10)
	v_add_co_u32_e32 v8, vcc, s37, v6
	global_load_dword v3, v[4:5], off offset:-4096
	s_nop 0
	global_load_dword v4, v[4:5], off
	s_waitcnt vmcnt(11)
	v_addc_co_u32_e32 v9, vcc, 0, v7, vcc
	global_load_dword v5, v[8:9], off
	v_add_co_u32_e32 v8, vcc, 0x4000, v6
	s_lshl_b32 s8, s62, 1
	s_nop 0
	v_addc_co_u32_e32 v9, vcc, 0, v7, vcc
	v_add_co_u32_e32 v12, vcc, s55, v6
	global_load_dword v8, v[8:9], off
	s_nop 0
	v_addc_co_u32_e32 v13, vcc, 0, v7, vcc
	v_add_co_u32_e32 v6, vcc, 0x7000, v6
	global_load_dword v9, v[12:13], off offset:-4096
	s_nop 0
	global_load_dword v12, v[12:13], off
	v_addc_co_u32_e32 v7, vcc, 0, v7, vcc
	global_load_dword v13, v[6:7], off
	v_add_u32_e32 v7, 0, v10
	v_lshlrev_b32_e32 v6, 8, v0
	v_lshlrev_b32_e32 v10, 2, v1
	v_add3_u32 v6, v7, v6, v10
	v_mul_lo_u32 v10, v1, s22
	s_add_i32 s8, s89, s8
	v_add_u32_e32 v7, v7, v10
	v_lshlrev_b32_e32 v10, 1, v0
	s_mov_b32 s9, s75
	s_waitcnt vmcnt(0)
	s_branch .LBB0_348

; __device__ void transpose_job(const int bid, const int nblk, float* tile, const float* __restrict__ src, bf16_t* __restrict__ dst, int K, int N, int nb, long dstB, float scale) {
;     ...
;     while (t < tot) {
;         const int b = t / per, l = t - b * per, k0 = (l / tn) * 64, n0 = (l % tn) * 64;
;         bf16_t* d = dst + (long)b * dstB;
; #pragma unroll
;         for (int i = 0; i < 8; ++i) tile[(kk + 8 * i) * 65 + nn] = r[i];
;         __syncthreads();
;         const int t2 = t + nblk;
;         if (t2 < tot) { const int b2 = t2 / per, l2 = t2 - b2 * per, k2 = (l2 / tn) * 64, n2 = (l2 % tn) * 64; const float* s2 = src + (long)b2 * K * N;
; #pragma unroll
;             for (int i = 0; i < 8; ++i) r[i] = s2[(long)(k2 + kk + 8 * i) * N + n2 + nn]; }
.LBB0_348:
	s_add_i32 s10, s8, s9
	s_cmpk_gt_i32 s10, 0x4f
	s_waitcnt vmcnt(15)
	ds_write_b32 v7, v2
	s_waitcnt vmcnt(14)
	ds_write_b32 v7, v3 offset:2080
	s_waitcnt vmcnt(13)
	ds_write_b32 v7, v4 offset:4160
	s_waitcnt vmcnt(12)
	ds_write_b32 v7, v5 offset:6240
	s_waitcnt vmcnt(11)
	ds_write_b32 v7, v8 offset:8320
	s_waitcnt vmcnt(10)
	ds_write_b32 v7, v9 offset:10400
	s_waitcnt vmcnt(9)
	ds_write_b32 v7, v12 offset:12480
	s_waitcnt vmcnt(8)
	ds_write_b32 v7, v13 offset:14560
	s_waitcnt lgkmcnt(0)
	s_barrier
	s_cbranch_scc1 .LBB0_347
	s_ashr_i32 s11, s10, 31
	s_lshr_b32 s11, s11, 30
	s_add_i32 s11, s10, s11
	s_ashr_i32 s12, s11, 2
	s_and_b32 s11, s11, -4
	s_sub_i32 s10, s10, s11
	s_lshr_b32 s11, s10, 31
	s_add_i32 s11, s10, s11
	s_lshl_b32 s13, s11, 5
	s_and_b32 s11, s11, 0x3fffffe
	s_and_b32 s14, s13, 0xffffffc0
	s_sub_i32 s10, s10, s11
	s_ashr_i32 s13, s12, 31
	s_lshl_b32 s10, s10, 6
	s_lshl_b64 s[12:13], s[12:13], 16
	s_add_u32 s12, s6, s12
	s_addc_u32 s13, s7, s13
	s_ashr_i32 s11, s10, 31
	s_lshl_b64 s[10:11], s[10:11], 2
	v_add_u32_e32 v2, s14, v1
	s_add_u32 s10, s12, s10
	s_addc_u32 s11, s13, s11
	v_lshlrev_b32_e32 v4, 2, v0
	v_mov_b32_e32 v5, v11
	v_ashrrev_i32_e32 v3, 31, v2
	v_lshl_add_u64 v[4:5], s[10:11], 0, v[4:5]
	v_lshlrev_b64 v[2:3], 9, v[2:3]
	v_lshl_add_u64 v[14:15], v[4:5], 0, v[2:3]
	v_add_co_u32_e32 v4, vcc, s76, v14
	global_load_dword v2, v[14:15], off
	s_nop 0
	v_addc_co_u32_e32 v5, vcc, 0, v15, vcc
	v_add_co_u32_e32 v8, vcc, s37, v14
	global_load_dword v3, v[4:5], off offset:-4096
	s_nop 0
	global_load_dword v4, v[4:5], off
	v_addc_co_u32_e32 v9, vcc, 0, v15, vcc
	global_load_dword v5, v[8:9], off
	v_add_co_u32_e32 v8, vcc, 0x4000, v14
	s_nop 1
	v_addc_co_u32_e32 v9, vcc, 0, v15, vcc
	v_add_co_u32_e32 v12, vcc, 0x5000, v14
	global_load_dword v8, v[8:9], off
	s_nop 0
	v_addc_co_u32_e32 v13, vcc, 0, v15, vcc
	global_load_dword v9, v[12:13], off
	v_add_co_u32_e32 v12, vcc, 0x6000, v14
	s_nop 1
	v_addc_co_u32_e32 v13, vcc, 0, v15, vcc
	v_add_co_u32_e32 v14, vcc, 0x7000, v14
	global_load_dword v12, v[12:13], off
	s_nop 0
	v_addc_co_u32_e32 v15, vcc, 0, v15, vcc
	global_load_dword v13, v[14:15], off
	s_branch .LBB0_347

; __device__ __forceinline__ int tid_() { int t = threadIdx.x; asm volatile("" : "+v"(t)); return t; }
; __device__ void transpose_job(const int bid, const int nblk, float* tile, const float* __restrict__ src, bf16_t* __restrict__ dst, int K, int N, int nb, long dstB, float scale) {
;     const int tk = K / 64, tn = N / 64, per = tk * tn, tot = per * nb, tid = tid_();
;     const int kk = tid >> 6, nn = tid & 63;
;     float r[8];
;     int t = bid;
;     if (t < tot) { const int b = t / per, l = t - b * per, k0 = (l / tn) * 64, n0 = (l % tn) * 64; const float* s = src + (long)b * K * N;
; #pragma unroll
;         for (int i = 0; i < 8; ++i) r[i] = s[(long)(k0 + kk + 8 * i) * N + n0 + nn]; }
.LBB0_351:
	v_mov_b32_e32 v0, v169
	s_andn2_b64 vcc, exec, s[4:5]
	s_cbranch_vccnz .LBB0_356
	s_waitcnt lgkmcnt(0)
	s_add_u32 s2, s2, 0x8000
	v_readlane_b32 s6, v254, 29
	s_addc_u32 s3, s3, 0
	s_mov_b32 s8, s6
	s_ashr_i32 s6, s6, 31
	v_readlane_b32 s7, v254, 30
	s_lshr_b32 s6, s6, 30
	s_add_i32 s7, s8, s6
	s_ashr_i32 s6, s7, 2
	s_and_b32 s7, s7, -4
	s_sub_i32 s7, s8, s7
	s_lshr_b32 s8, s7, 31
	s_load_dwordx2 s[4:5], s[26:27], 0x60
	s_add_i32 s8, s7, s8
	s_lshl_b32 s9, s8, 5
	s_and_b32 s8, s8, 0x3fffffe
	s_sub_i32 s7, s7, s8
	s_lshl_b32 s8, s7, 6
	s_ashr_i32 s7, s6, 31
	s_andn2_b32 s9, s9, 63
	s_lshl_b64 s[6:7], s[6:7], 16
	v_ashrrev_i32_e32 v1, 6, v0
	s_waitcnt lgkmcnt(0)
	s_add_u32 s10, s4, s6
	s_addc_u32 s11, s5, s7
	s_waitcnt vmcnt(0)
	v_add_u32_e32 v2, s9, v1
	s_ashr_i32 s9, s8, 31
	s_lshl_b64 s[6:7], s[8:9], 2
	v_and_b32_e32 v0, 63, v0
	s_add_u32 s6, s10, s6
	s_addc_u32 s7, s11, s7
	v_lshlrev_b32_e32 v10, 2, v0
	s_waitcnt vmcnt(14)
	v_ashrrev_i32_e32 v3, 31, v2
	s_waitcnt vmcnt(12)
	v_lshl_add_u64 v[4:5], s[6:7], 0, v[10:11]
	v_lshlrev_b64 v[2:3], 9, v[2:3]
	s_waitcnt vmcnt(10)
	v_lshl_add_u64 v[6:7], v[4:5], 0, v[2:3]
	v_add_co_u32_e32 v4, vcc, s76, v6
	global_load_dword v2, v[6:7], off
	s_nop 0
	v_addc_co_u32_e32 v5, vcc, 0, v7, vcc
	s_waitcnt vmcnt(10)
	v_add_co_u32_e32 v8, vcc, s37, v6
	global_load_dword v3, v[4:5], off offset:-4096
	s_nop 0
	global_load_dword v4, v[4:5], off
	s_waitcnt vmcnt(11)
	v_addc_co_u32_e32 v9, vcc, 0, v7, vcc
	global_load_dword v5, v[8:9], off
	v_add_co_u32_e32 v8, vcc, 0x4000, v6
	s_lshl_b32 s6, s62, 1
	s_nop 0
	v_addc_co_u32_e32 v9, vcc, 0, v7, vcc
	v_add_co_u32_e32 v12, vcc, s55, v6
	global_load_dword v8, v[8:9], off
	s_nop 0
	v_addc_co_u32_e32 v13, vcc, 0, v7, vcc
	v_add_co_u32_e32 v6, vcc, 0x7000, v6
	global_load_dword v9, v[12:13], off offset:-4096
	s_nop 0
	global_load_dword v12, v[12:13], off
	v_addc_co_u32_e32 v7, vcc, 0, v7, vcc
	global_load_dword v13, v[6:7], off
	v_add_u32_e32 v7, 0, v10
	v_lshlrev_b32_e32 v6, 8, v0
	v_lshlrev_b32_e32 v10, 2, v1
	v_add3_u32 v6, v7, v6, v10
	v_mul_lo_u32 v10, v1, s22
	s_add_i32 s6, s89, s6
	v_add_u32_e32 v7, v7, v10
	v_lshlrev_b32_e32 v10, 1, v0
	s_mov_b32 s7, s75
	s_waitcnt vmcnt(0)
	s_branch .LBB0_354

; __device__ void transpose_job(const int bid, const int nblk, float* tile, const float* __restrict__ src, bf16_t* __restrict__ dst, int K, int N, int nb, long dstB, float scale) {
;     ...
;     while (t < tot) {
;         const int b = t / per, l = t - b * per, k0 = (l / tn) * 64, n0 = (l % tn) * 64;
;         bf16_t* d = dst + (long)b * dstB;
; #pragma unroll
;         for (int i = 0; i < 8; ++i) tile[(kk + 8 * i) * 65 + nn] = r[i];
;         __syncthreads();
;         const int t2 = t + nblk;
;         if (t2 < tot) { const int b2 = t2 / per, l2 = t2 - b2 * per, k2 = (l2 / tn) * 64, n2 = (l2 % tn) * 64; const float* s2 = src + (long)b2 * K * N;
; #pragma unroll
;             for (int i = 0; i < 8; ++i) r[i] = s2[(long)(k2 + kk + 8 * i) * N + n2 + nn]; }
.LBB0_354:
	s_add_i32 s8, s6, s7
	s_cmpk_gt_i32 s8, 0x4f
	s_waitcnt vmcnt(15)
	ds_write_b32 v7, v2
	s_waitcnt vmcnt(14)
	ds_write_b32 v7, v3 offset:2080
	s_waitcnt vmcnt(13)
	ds_write_b32 v7, v4 offset:4160
	s_waitcnt vmcnt(12)
	ds_write_b32 v7, v5 offset:6240
	s_waitcnt vmcnt(11)
	ds_write_b32 v7, v8 offset:8320
	s_waitcnt vmcnt(10)
	ds_write_b32 v7, v9 offset:10400
	s_waitcnt vmcnt(9)
	ds_write_b32 v7, v12 offset:12480
	s_waitcnt vmcnt(8)
	ds_write_b32 v7, v13 offset:14560
	s_waitcnt lgkmcnt(0)
	s_barrier
	s_cbranch_scc1 .LBB0_353
	s_ashr_i32 s9, s8, 31
	s_lshr_b32 s9, s9, 30
	s_add_i32 s9, s8, s9
	s_ashr_i32 s10, s9, 2
	s_and_b32 s9, s9, -4
	s_sub_i32 s8, s8, s9
	s_lshr_b32 s9, s8, 31
	s_add_i32 s9, s8, s9
	s_lshl_b32 s11, s9, 5
	s_and_b32 s9, s9, 0x3fffffe
	s_and_b32 s12, s11, 0xffffffc0
	s_sub_i32 s8, s8, s9
	s_ashr_i32 s11, s10, 31
	s_lshl_b32 s8, s8, 6
	s_lshl_b64 s[10:11], s[10:11], 16
	s_add_u32 s10, s4, s10
	s_addc_u32 s11, s5, s11
	s_ashr_i32 s9, s8, 31
	s_lshl_b64 s[8:9], s[8:9], 2
	v_add_u32_e32 v2, s12, v1
	s_add_u32 s8, s10, s8
	s_addc_u32 s9, s11, s9
	v_lshlrev_b32_e32 v4, 2, v0
	v_mov_b32_e32 v5, v11
	v_ashrrev_i32_e32 v3, 31, v2
	v_lshl_add_u64 v[4:5], s[8:9], 0, v[4:5]
	v_lshlrev_b64 v[2:3], 9, v[2:3]
	v_lshl_add_u64 v[14:15], v[4:5], 0, v[2:3]
	v_add_co_u32_e32 v4, vcc, s76, v14
	global_load_dword v2, v[14:15], off
	s_nop 0
	v_addc_co_u32_e32 v5, vcc, 0, v15, vcc
	v_add_co_u32_e32 v8, vcc, s37, v14
	global_load_dword v3, v[4:5], off offset:-4096
	s_nop 0
	global_load_dword v4, v[4:5], off
	v_addc_co_u32_e32 v9, vcc, 0, v15, vcc
	global_load_dword v5, v[8:9], off
	v_add_co_u32_e32 v8, vcc, 0x4000, v14
	s_nop 1
	v_addc_co_u32_e32 v9, vcc, 0, v15, vcc
	v_add_co_u32_e32 v12, vcc, 0x5000, v14
	global_load_dword v8, v[8:9], off
	s_nop 0
	v_addc_co_u32_e32 v13, vcc, 0, v15, vcc
	global_load_dword v9, v[12:13], off
	v_add_co_u32_e32 v12, vcc, 0x6000, v14
	s_nop 1
	v_addc_co_u32_e32 v13, vcc, 0, v15, vcc
	v_add_co_u32_e32 v14, vcc, 0x7000, v14
	global_load_dword v12, v[12:13], off
	s_nop 0
	v_addc_co_u32_e32 v15, vcc, 0, v15, vcc
	global_load_dword v13, v[14:15], off
	s_branch .LBB0_353
